# one static s_setprio 1 for waves 4-7 at kernel entry for the whole kernel, all per-segment GEMM flips deleted (doc 7.4 steps a+b)
# baseline (speedup 1.0000x reference)
; #define LAS __attribute__((address_space(3)))
; __device__ __forceinline__ unsigned xb_add(unsigned* p, unsigned v) { return __hip_atomic_fetch_add(p, v, __ATOMIC_RELAXED, __HIP_MEMORY_SCOPE_AGENT); }
; __device__ __forceinline__ unsigned xb_xcc_id() { return (unsigned)__builtin_amdgcn_s_getreg((3 << 11) | 20) & 0xFu; }
; __global__ void __launch_bounds__(512, 2) hybrid_fwd(Params p) {
;     extern __shared__ __attribute__((aligned(16))) unsigned char lds_raw[];
;     LAS unsigned char* lds = (LAS unsigned char*)lds_raw;
;     cg::grid_group grid = cg::this_grid();
;     unsigned char* ws = p.ws;
;     XcdBarrier xb; xb.bar = (unsigned*)(ws + OFF_BAR); xb.x = xb_xcc_id();
;     if (threadIdx.x == 0) (void)xb_add(&xb.bar[XB_XCNT(xb.x)], 1u);
_Z10hybrid_fwd6Params:
	v_readfirstlane_b32 vcc_lo, v0
	s_nop 3
	s_bitcmp1_b32 vcc_lo, 8
	s_cbranch_scc0 .Lkprio_skip
	s_setprio 1
.Lkprio_skip:
	s_load_dwordx4 s[84:87], s[0:1], 0x88
	s_load_dword s3, s[0:1], 0x98
	s_mov_b64 s[74:75], s[0:1]
	s_add_u32 s12, s74, 0x98
	s_addc_u32 s13, s75, 0
	s_waitcnt lgkmcnt(0)
	s_add_u32 s78, s86, 0x180000
	s_getreg_b32 s0, hwreg(HW_REG_XCC_ID, 0, 4)
	v_and_b32_e32 v254, 0x3ff, v0
	s_mov_b32 s33, s2
	s_addc_u32 s79, s87, 0
	s_and_b32 s73, s0, 15
	v_cmp_eq_u32_e64 s[96:97], 0, v254
	s_and_saveexec_b64 s[4:5], s[96:97]
	s_cbranch_execz .LBB0_3
	s_mov_b64 s[6:7], exec
	v_mbcnt_lo_u32_b32 v1, s6, 0
	v_mbcnt_hi_u32_b32 v1, s7, v1
	v_cmp_eq_u32_e32 vcc, 0, v1
	s_and_b64 s[0:1], exec, vcc
	s_mov_b64 exec, s[0:1]
	s_cbranch_execz .LBB0_3
	s_lshl_b32 s0, s73, 8
	s_bcnt1_i32_b64 s1, s[6:7]
	v_mov_b32_e32 v1, s0
	v_mov_b32_e32 v2, s1
	global_atomic_add v1, v2, s[78:79] offset:1024
